# first seam uses the XCD barrier instead of cg grid sync
# baseline (speedup 1.0000x reference)
.LBB0_7:
	s_cmp_le_i32 s95, s94
	s_cbranch_scc1 .LBB0_700
	s_add_u32 s96, s92, 0x4400000
	s_addc_u32 s97, s93, 0
	s_add_u32 s4, s0, 0x100
	s_addc_u32 s5, s1, 0
	v_writelane_b32 v243, s4, 9
	s_load_dword s98, s[0:1], 0x100
	s_mov_b32 s35, 0
	v_writelane_b32 v243, s5, 10
	v_lshrrev_b32_e32 v1, 20, v0
	v_readlane_b32 s16, v243, 0
	s_cmpk_lt_i32 s16, 0x620
	s_cselect_b64 s[36:37], -1, 0
	s_add_u32 s9, s92, 0x22c80000
	s_addc_u32 s10, s93, 0
	s_add_u32 s4, s92, 0x21680000
	v_writelane_b32 v243, s4, 11
	s_addc_u32 s4, s93, 0
	s_add_u32 s41, s92, 0x1ea80000
	v_writelane_b32 v243, s4, 12
	s_addc_u32 s4, s93, 0
	v_writelane_b32 v243, s4, 13
	s_add_u32 s4, s92, 0x1d480000
	v_writelane_b32 v243, s4, 14
	s_addc_u32 s4, s93, 0
	s_add_u32 s79, s92, 0x1a880000
	v_writelane_b32 v243, s4, 15
	s_addc_u32 s4, s93, 0
	v_writelane_b32 v243, s4, 16
	s_add_u32 s4, s92, 0x25584000
	v_writelane_b32 v243, s4, 17
	s_addc_u32 s4, s93, 0
	v_writelane_b32 v243, s4, 18
	s_add_u32 s4, s92, 0x25771000
	s_addc_u32 s5, s93, 0
	v_writelane_b32 v243, s4, 19
	v_lshrrev_b32_e32 v0, 10, v0
	v_or_b32_e32 v0, v0, v1
	v_writelane_b32 v243, s5, 20
	s_add_u32 s4, s92, 0x25661000
	s_addc_u32 s5, s93, 0
	v_writelane_b32 v243, s4, 21
	s_lshl_b32 s11, s16, 9
	s_waitcnt lgkmcnt(0)
	s_lshl_b32 s99, s98, 3
	v_writelane_b32 v243, s5, 22
	s_lshl_b32 s4, s98, 9
	v_writelane_b32 v243, s4, 23
	s_lshl_b32 s4, s16, 3
	v_writelane_b32 v243, s4, 24
	s_sub_i32 s4, s16, s98
	s_add_i32 s6, s4, 32
	s_max_i32 s4, s6, 0
	s_lshr_b32 s34, s4, 3
	s_lshl_b64 s[4:5], s[34:35], 21
	s_and_b32 s7, s6, 7
	s_cmp_gt_i32 s6, -1
	s_cselect_b32 s6, s7, -1
	v_writelane_b32 v243, s6, 25
	s_add_u32 s6, s92, 0x8800000
	s_addc_u32 s7, s93, 0
	v_writelane_b32 v243, s6, 26
	s_mov_b32 s52, s94
	v_mov_b32_e32 v137, 0
	v_writelane_b32 v243, s7, 27
	s_add_u32 s6, s92, 0x25650000
	v_writelane_b32 v243, s6, 28
	s_addc_u32 s6, s93, 0
	v_writelane_b32 v243, s6, 29
	s_add_u32 s6, s92, 0x25480000
	s_addc_u32 s7, s93, 0
	v_writelane_b32 v243, s6, 30
	v_mov_b32_e32 v162, 0x3727c5ac
	v_mov_b32_e32 v163, 1
	v_writelane_b32 v243, s7, 31
	s_add_u32 s6, s92, 0x18f80000
	s_addc_u32 s7, s93, 0
	v_writelane_b32 v243, s6, 32
	v_mov_b32_e32 v165, 0x41b17218
	s_movk_i32 s76, 0x104
	v_writelane_b32 v243, s7, 33
	s_add_u32 s6, s92, 0x255d9000
	s_addc_u32 s7, s93, 0
	v_writelane_b32 v243, s6, 34
	s_add_u32 s12, s92, 0x1a080000
	s_addc_u32 s13, s93, 0
	v_writelane_b32 v243, s7, 35
	s_lshl_b64 s[6:7], s[34:35], 20
	v_writelane_b32 v243, s12, 36
	s_add_u32 s12, s12, s6
	v_writelane_b32 v243, s13, 37
	s_addc_u32 s13, s13, s7
	v_writelane_b32 v243, s12, 38
	s_add_u32 s4, s9, s4
	s_addc_u32 s5, s10, s5
	v_writelane_b32 v243, s13, 39
	v_writelane_b32 v243, s9, 40
	v_writelane_b32 v243, s10, 41
	v_writelane_b32 v243, s4, 42
	s_movk_i32 s77, 0x3fff
	s_mov_b32 s40, 0x800000
	v_writelane_b32 v243, s5, 43
	s_add_u32 s4, s92, 0x1a480000
	s_addc_u32 s5, s93, 0
	v_writelane_b32 v243, s4, 44
	s_add_u32 s4, s4, s6
	v_writelane_b32 v243, s5, 45
	s_addc_u32 s5, s5, s7
	v_writelane_b32 v243, s4, 46
	s_movk_i32 s42, 0x1600
	s_movk_i32 s43, 0xff7f
	v_writelane_b32 v243, s5, 47
	s_add_u32 s4, s90, s6
	s_addc_u32 s5, s91, s7
	s_add_u32 s6, s4, 0x6688000
	s_addc_u32 s7, s5, 0
	v_writelane_b32 v243, s6, 48
	s_add_u32 s4, s4, 0x6a88000
	s_addc_u32 s5, s5, 0
	v_writelane_b32 v243, s7, 49
	v_writelane_b32 v243, s4, 50
	s_mov_b32 s7, s35
	s_mov_b32 s33, 0xff800000
	v_writelane_b32 v243, s5, 51
	s_add_u32 s4, s92, 0xe580000
	s_addc_u32 s5, s93, 0
	v_writelane_b32 v243, s4, 52
	s_mov_b32 s22, 0x3db504f3
	s_mov_b64 s[26:27], 0x80
	v_writelane_b32 v243, s5, 53
	s_add_u32 s4, s92, 0x15c80000
	s_addc_u32 s5, s93, 0
	s_sub_i32 s6, s16, 64
	s_sub_i32 s12, s98, 64
	v_writelane_b32 v243, s4, 54
	s_cmp_gt_i32 s98, 64
	s_nop 0
	v_writelane_b32 v243, s5, 55
	s_cselect_b64 s[4:5], -1, 0
	s_cmp_gt_i32 s16, 63
	s_cselect_b64 s[14:15], -1, 0
	v_writelane_b32 v243, s14, 56
	s_and_b64 s[4:5], s[14:15], s[4:5]
	s_nop 0
	v_writelane_b32 v243, s15, 57
	v_writelane_b32 v243, s4, 58
	s_nop 1
	v_writelane_b32 v243, s5, 59
	s_add_u32 s4, s92, 0x24e80000
	v_writelane_b32 v243, s4, 60
	s_addc_u32 s4, s93, 0
	v_writelane_b32 v243, s4, 61
	s_add_u32 s4, s92, 0x24880000
	v_writelane_b32 v243, s4, 62
	s_addc_u32 s4, s93, 0
	v_writelane_b32 v243, s4, 63
	s_add_u32 s4, s92, 0x24280000
	v_writelane_b32 v242, s4, 0
	s_addc_u32 s4, s93, 0
	v_writelane_b32 v242, s4, 1
	s_add_u32 s4, s92, 0x23480000
	v_writelane_b32 v242, s4, 2
	s_addc_u32 s4, s93, 0
	v_writelane_b32 v242, s4, 3
	s_mov_b32 s4, s6
	v_writelane_b32 v242, s4, 4
	s_ashr_i32 s13, s12, 31
	s_nop 0
	v_writelane_b32 v242, s5, 5
	s_lshl_b64 s[4:5], s[6:7], 9
	v_writelane_b32 v242, s4, 6
	s_nop 1
	v_writelane_b32 v242, s5, 7
	s_mov_b32 s4, s12
	v_writelane_b32 v242, s4, 8
	s_nop 1
	v_writelane_b32 v242, s5, 9
	s_lshl_b64 s[4:5], s[12:13], 9
	v_writelane_b32 v242, s4, 10
	s_nop 1
	v_writelane_b32 v242, s5, 11
	s_add_u32 s4, s90, 0x4688000
	s_addc_u32 s5, s91, 0
	v_writelane_b32 v242, s4, 12
	s_nop 1
	v_writelane_b32 v242, s5, 13
	s_add_u32 s4, s90, 0x5688000
	s_addc_u32 s5, s91, 0
	v_writelane_b32 v242, s4, 14
	s_nop 1
	v_writelane_b32 v242, s5, 15
	s_mul_hi_i32 s4, s16, 0x55555556
	s_lshr_b32 s5, s4, 31
	s_add_i32 s4, s4, s5
	s_mul_i32 s4, s4, 3
	s_sub_i32 s4, s16, s4
	s_add_i32 s5, s98, -1
	s_cmp_eq_u32 s4, 1
	v_writelane_b32 v242, s5, 16
	s_cselect_b32 s5, 1, 3
	s_cmp_lg_u32 s4, 0
	s_cselect_b32 s4, s5, 0
	v_writelane_b32 v242, s4, 17
	s_add_u32 s4, s90, 0x4400000
	v_writelane_b32 v242, s4, 18
	s_addc_u32 s4, s91, 0
	v_writelane_b32 v242, s4, 19
	s_add_u32 s4, s90, 0x4408000
	v_writelane_b32 v242, s4, 20
	s_addc_u32 s4, s91, 0
	v_writelane_b32 v242, s4, 21
	s_add_u32 s4, s92, 0x25580200
	s_addc_u32 s5, s93, 0
	v_writelane_b32 v242, s4, 22
	s_nop 1
	v_writelane_b32 v242, s5, 23
	s_add_u32 s4, s92, 0x25580400
	s_addc_u32 s5, s93, 0
	v_writelane_b32 v242, s4, 24
	s_nop 1
	v_writelane_b32 v242, s5, 25
	s_add_u32 s4, s92, 0x25580500
	s_addc_u32 s5, s93, 0
	v_writelane_b32 v242, s4, 26
	s_nop 1
	v_writelane_b32 v242, s5, 27
	s_add_u32 s4, s92, 0x25580600
	s_addc_u32 s5, s93, 0
	v_writelane_b32 v242, s4, 28
	s_nop 1
	v_writelane_b32 v242, s5, 29
	s_add_u32 s4, s92, 0x25580700
	s_addc_u32 s5, s93, 0
	v_writelane_b32 v242, s4, 30
	s_nop 1
	v_writelane_b32 v242, s5, 31
	s_add_u32 s4, s92, 0x25580800
	s_addc_u32 s5, s93, 0
	v_writelane_b32 v242, s4, 32
	s_nop 1
	v_writelane_b32 v242, s5, 33
	s_add_u32 s4, s92, 0x25580900
	s_addc_u32 s5, s93, 0
	v_writelane_b32 v242, s4, 34
	s_nop 1
	v_writelane_b32 v242, s5, 35
	s_add_u32 s4, s92, 0x25580a00
	s_addc_u32 s5, s93, 0
	v_writelane_b32 v242, s4, 36
	s_nop 1
	v_writelane_b32 v242, s5, 37
	s_add_u32 s4, s92, 0x25580b00
	s_addc_u32 s5, s93, 0
	v_writelane_b32 v242, s4, 38
	s_nop 1
	v_writelane_b32 v242, s5, 39
	s_add_u32 s4, s92, 0x25580c00
	s_addc_u32 s5, s93, 0
	v_writelane_b32 v242, s4, 40
	s_nop 1
	v_writelane_b32 v242, s5, 41
	s_add_u32 s4, s92, 0x25580d00
	s_addc_u32 s5, s93, 0
	v_writelane_b32 v242, s4, 42
	s_nop 1
	v_writelane_b32 v242, s5, 43
	s_add_u32 s4, s92, 0x25580e00
	s_addc_u32 s5, s93, 0
	v_writelane_b32 v242, s4, 44
	s_nop 1
	v_writelane_b32 v242, s5, 45
	s_add_u32 s4, s92, 0x25580f00
	s_addc_u32 s5, s93, 0
	v_writelane_b32 v242, s4, 46
	s_nop 1
	v_writelane_b32 v242, s5, 47
	s_add_u32 s4, s92, 0x25581000
	s_addc_u32 s5, s93, 0
	v_writelane_b32 v242, s4, 48
	s_nop 1
	v_writelane_b32 v242, s5, 49
	s_add_u32 s4, s92, 0x25581100
	s_addc_u32 s5, s93, 0
	v_writelane_b32 v242, s4, 50
	s_nop 1
	v_writelane_b32 v242, s5, 51
	s_add_u32 s4, s92, 0x25581200
	s_addc_u32 s5, s93, 0
	v_writelane_b32 v242, s4, 52
	s_nop 1
	v_writelane_b32 v242, s5, 53
	s_add_u32 s4, s92, 0x25581300
	s_addc_u32 s5, s93, 0
	v_writelane_b32 v242, s4, 54
	s_cmp_eq_u32 s8, 15
	s_nop 0
	v_writelane_b32 v242, s5, 55
	s_cselect_b64 s[4:5], -1, 0
	v_writelane_b32 v242, s4, 56
	s_cmp_eq_u32 s8, 14
	s_nop 0
	v_writelane_b32 v242, s5, 57
	s_cselect_b64 s[4:5], -1, 0
	v_writelane_b32 v242, s4, 58
	s_cmp_eq_u32 s8, 13
	s_nop 0
	v_writelane_b32 v242, s5, 59
	s_cselect_b64 s[4:5], -1, 0
	v_writelane_b32 v242, s4, 60
	s_cmp_eq_u32 s8, 12
	s_nop 0
	v_writelane_b32 v242, s5, 61
	s_cselect_b64 s[4:5], -1, 0
	v_writelane_b32 v242, s4, 62
	s_cmp_eq_u32 s8, 11
	s_nop 0
	v_writelane_b32 v242, s5, 63
	s_cselect_b64 s[4:5], -1, 0
	v_writelane_b32 v241, s4, 0
	s_cmp_eq_u32 s8, 10
	s_nop 0
	v_writelane_b32 v241, s5, 1
	s_cselect_b64 s[4:5], -1, 0
	v_writelane_b32 v241, s4, 2
	s_cmp_eq_u32 s8, 9
	s_nop 0
	v_writelane_b32 v241, s5, 3
	s_cselect_b64 s[4:5], -1, 0
	v_writelane_b32 v241, s4, 4
	s_cmp_eq_u32 s8, 8
	s_nop 0
	v_writelane_b32 v241, s5, 5
	s_cselect_b64 s[4:5], -1, 0
	v_writelane_b32 v241, s4, 6
	s_cmp_eq_u32 s8, 7
	s_nop 0
	v_writelane_b32 v241, s5, 7
	s_cselect_b64 s[4:5], -1, 0
	v_writelane_b32 v241, s4, 8
	s_cmp_eq_u32 s8, 6
	s_nop 0
	v_writelane_b32 v241, s5, 9
	s_cselect_b64 s[4:5], -1, 0
	v_writelane_b32 v241, s4, 10
	s_cmp_eq_u32 s8, 5
	s_nop 0
	v_writelane_b32 v241, s5, 11
	s_cselect_b64 s[4:5], -1, 0
	v_writelane_b32 v241, s4, 12
	s_cmp_eq_u32 s8, 4
	s_nop 0
	v_writelane_b32 v241, s5, 13
	s_cselect_b64 s[4:5], -1, 0
	v_writelane_b32 v241, s4, 14
	s_cmp_eq_u32 s8, 3
	s_nop 0
	v_writelane_b32 v241, s5, 15
	s_cselect_b64 s[4:5], -1, 0
	v_writelane_b32 v241, s4, 16
	s_cmp_eq_u32 s8, 2
	s_nop 0
	v_writelane_b32 v241, s5, 17
	s_cselect_b64 s[4:5], -1, 0
	v_writelane_b32 v241, s4, 18
	s_cmp_eq_u32 s8, 1
	s_nop 0
	v_writelane_b32 v241, s5, 19
	s_cselect_b64 s[4:5], -1, 0
	v_writelane_b32 v241, s4, 20
	s_cmp_eq_u32 s8, 0
	s_nop 0
	v_writelane_b32 v241, s5, 21
	s_cselect_b64 s[4:5], -1, 0
	v_writelane_b32 v241, s4, 22
	s_nop 1
	v_writelane_b32 v241, s5, 23
	s_lshl_b32 s4, s8, 8
	s_add_u32 s2, s2, s4
	s_addc_u32 s3, s3, 0
	s_add_u32 s2, s2, 0x1400
	s_addc_u32 s3, s3, 0
	v_writelane_b32 v241, s2, 24
	s_nop 1
	v_writelane_b32 v241, s3, 25
	s_movk_i32 s2, 0x3ff
	v_and_or_b32 v0, v0, s2, v147
	s_add_u32 s2, s92, 0x25583400
	s_addc_u32 s3, s93, 0
	v_writelane_b32 v241, s2, 26
	s_nop 1
	v_writelane_b32 v241, s3, 27
	s_abs_i32 s2, s98
	v_cvt_f32_u32_e32 v1, s2
	v_writelane_b32 v241, s2, 28
	s_sub_i32 s2, 0, s2
	v_rcp_iflag_f32_e32 v1, v1
	s_nop 0
	v_mul_f32_e32 v1, 0x4f7ffffe, v1
	v_cvt_u32_f32_e32 v1, v1
	s_nop 0
	v_readfirstlane_b32 s3, v1
	s_mul_i32 s2, s2, s3
	s_mul_hi_u32 s2, s3, s2
	s_add_i32 s2, s3, s2
	v_writelane_b32 v241, s2, 29
	s_lshl_b32 s2, s98, 11
	s_add_i32 s2, s2, 0xfffe0000
	v_writelane_b32 v241, s2, 30
	s_ashr_i32 s2, s98, 31
	v_writelane_b32 v241, s2, 31
	v_writelane_b32 v241, s11, 32
	s_add_i32 s2, s11, 0xffff8000
	v_writelane_b32 v241, s2, 33
	s_add_i32 s2, 0, 0x20000
	v_writelane_b32 v241, s2, 34
	s_add_i32 s2, 0, 0x20004
	v_writelane_b32 v241, s2, 35
	v_cmp_eq_u32_e64 s[2:3], 0, v147
	s_load_dwordx16 s[4:19], s[0:1], 0x0
	v_mbcnt_lo_u32_b32 v1, -1, 0
	v_writelane_b32 v241, s2, 36
	v_mbcnt_hi_u32_b32 v164, -1, v1
	s_nop 0
	v_writelane_b32 v241, s3, 37
	v_cmp_eq_u32_e64 s[2:3], 0, v0
	s_nop 1
	v_writelane_b32 v241, s2, 38
	s_nop 1
	v_writelane_b32 v241, s3, 39
	s_waitcnt lgkmcnt(0)
	v_writelane_b32 v241, s4, 40
	s_nop 1
	v_writelane_b32 v241, s5, 41
	v_writelane_b32 v241, s6, 42
	v_writelane_b32 v241, s7, 43
	v_writelane_b32 v241, s8, 44
	v_writelane_b32 v241, s9, 45
	v_writelane_b32 v241, s10, 46
	v_writelane_b32 v241, s11, 47
	v_writelane_b32 v241, s12, 48
	v_writelane_b32 v241, s13, 49
	v_writelane_b32 v241, s14, 50
	v_writelane_b32 v241, s15, 51
	v_writelane_b32 v241, s16, 52
	v_writelane_b32 v241, s17, 53
	v_writelane_b32 v241, s18, 54
	v_writelane_b32 v241, s19, 55
	s_load_dwordx16 s[60:75], s[0:1], 0x40
	s_load_dwordx16 s[4:19], s[0:1], 0x80
	s_waitcnt lgkmcnt(0)
	v_writelane_b32 v241, s4, 56
	s_nop 1
	v_writelane_b32 v240, s12, 0
	v_writelane_b32 v240, s13, 1
	v_writelane_b32 v240, s14, 2
	v_writelane_b32 v240, s15, 3
	v_writelane_b32 v240, s16, 4
	v_writelane_b32 v240, s17, 5
	v_writelane_b32 v240, s18, 6
	v_writelane_b32 v240, s19, 7
	v_writelane_b32 v240, s41, 8
	v_writelane_b32 v240, s88, 9
	v_writelane_b32 v241, s5, 57
	v_writelane_b32 v241, s6, 58
	v_writelane_b32 v240, s89, 10
	v_writelane_b32 v240, s90, 11
	v_writelane_b32 v240, s91, 12
	v_writelane_b32 v240, s92, 13
	v_writelane_b32 v240, s93, 14
	v_writelane_b32 v240, s94, 15
	v_writelane_b32 v240, s95, 16
	v_writelane_b32 v240, s96, 17
	v_writelane_b32 v241, s7, 59
	v_writelane_b32 v241, s8, 60
	v_writelane_b32 v240, s97, 18
	v_writelane_b32 v240, s98, 19
	v_writelane_b32 v241, s9, 61
	v_writelane_b32 v240, s36, 20
	v_writelane_b32 v241, s10, 62
	v_writelane_b32 v241, s11, 63
	v_writelane_b32 v240, s37, 21
	v_writelane_b32 v240, s79, 22
	s_branch .LBB0_13
.LBB0_11:
	s_mov_b64 s[0:1], 0
	s_waitcnt lgkmcnt(0)

.LBB0_650:
	s_add_i32 s14, s52, 1
	s_cmp_ge_i32 s14, s95
	s_mov_b64 s[0:1], -1
	s_cbranch_scc1 .LBB0_12
	s_waitcnt vmcnt(0)
	s_waitcnt vmcnt(0) lgkmcnt(0)
	s_barrier
	s_mov_b64 s[0:1], exec
	v_readlane_b32 s2, v241, 36
	v_readlane_b32 s3, v241, 37
	s_and_b64 s[2:3], s[0:1], s[2:3]
	s_mov_b64 exec, s[2:3]
	s_cbranch_execz .LBB0_684
	v_readlane_b32 s2, v241, 34
	s_waitcnt vmcnt(0) expcnt(0) lgkmcnt(0)
	s_nop 0
	v_mov_b32_e32 v0, s2
	ds_read_b32 v1, v0
	v_readlane_b32 s2, v241, 35
	s_waitcnt lgkmcnt(0)
	v_cmp_ne_u32_e32 vcc, 0, v1
	v_mov_b32_e32 v0, s2
	ds_read_b32 v0, v0
	s_cbranch_vccnz .LBB0_668
	v_readlane_b32 s4, v243, 9
	v_readlane_b32 s5, v243, 10
	s_load_dwordx2 s[2:3], s[4:5], 0x0
	s_nop 0
	s_load_dword s4, s[4:5], 0x8
	s_mov_b32 s9, 1
	s_waitcnt lgkmcnt(0)
	s_mul_i32 s8, s3, s2
	s_mul_i32 s8, s8, s4
	s_branch .LBB0_656

.LBB0_684:
	s_or_b64 exec, exec, s[0:1]
	s_barrier
	s_branch .LBB0_11
